# scan loops: issue fragment LDS reads ahead of next-chunk global prefetch block
# baseline (speedup 1.0000x reference)
; #define LAS __attribute__((address_space(3)))
; __device__ __forceinline__ void mixer_hg2(const Args& a, Frame& F, bool ctx_out) {
;     ...
;             H2_STAGE(u);
;             MX_BAR();
;             { const int cn = (c + PF < NCH) ? c + PF : NCH - 1; H2_LOAD(cn, u); }
;             f32x4 fe, fu;
;             {
;                 unsigned one2_ = 0x3F803F80u; asm volatile("" : "+v"(one2_));
;                 typedef unsigned u4_ __attribute__((ext_vector_type(4)));
;                 const mx_bf16x8 ones = __builtin_bit_cast(mx_bf16x8, (u4_){one2_, one2_, one2_, one2_});
;                 const mx_bf16x8 a0 = frag_tr(L + 2 * IMG, QS, 0, 16 * w, lane), a1 = frag_tr(L + 2 * IMG, QS, 32, 16 * w, lane);
;                 const f32x4 z = ZERO4;
;                 f32x4 ct[4];
;                 ct[0] = MX_MFMA(a0, bt0, z); ct[1] = MX_MFMA(a0, bt1, z);
;                 const f32x4 cref = MX_MFMA(a0, ones, z);
;                 ct[2] = MX_MFMA(a1, bt0, cref); ct[3] = MX_MFMA(a1, bt1, cref);
;                 const f32x4 cend = MX_MFMA(a1, ones, cref);
;                 fe = (f32x4){__expf(cend[0]), __expf(cend[1]), __expf(cend[2]), __expf(cend[3])};
;                 fu = (f32x4){__expf(cend[0] - cref[0]), __expf(cend[1] - cref[1]), __expf(cend[2] - cref[2]), __expf(cend[3] - cref[3])};
;                 const f32x4 fs = {__expf(cref[0]), __expf(cref[1]), __expf(cref[2]), __expf(cref[3])};
; #pragma unroll
;                 for (int te = 0; te < 4; ++te) { const f32x4 s = accS[te] * fs; v2u sw; sw.x = pk2(s[0], s[1]); sw.y = pk2(s[2], s[3]);
;                     *(LAS v2u*)(L + O_ST + (16 * te + i) * QS + (16 * w + 4 * g) * 2) = sw; }
; #pragma unroll
;                 for (int t = 0; t < 4; ++t) {
;                     LAS unsigned char* pq = L + (16 * t + i) * QS + (16 * w + 4 * g) * 2;
;                     const v2u qw = *(const LAS v2u*)pq, kw = *(const LAS v2u*)(pq + IMG);
;                     const f32x4 dd = ct[t] - cref;
;                     const f32x4 tt = (f32x4){__builtin_amdgcn_fmed3f(dd[0], -80.f, 80.f), __builtin_amdgcn_fmed3f(dd[1], -80.f, 80.f), __builtin_amdgcn_fmed3f(dd[2], -80.f, 80.f), __builtin_amdgcn_fmed3f(dd[3], -80.f, 80.f)} * 1.4426950408889634f;
;                     const f32x4 e1 = {__builtin_amdgcn_exp2f(tt[0]), __builtin_amdgcn_exp2f(tt[1]), __builtin_amdgcn_exp2f(tt[2]), __builtin_amdgcn_exp2f(tt[3])};
.LBB0_512:
	s_add_i32 s29, s31, 1
	s_add_i32 s36, s30, -1
	v_sub_co_u32_e64 v122, s[34:35], s31, 3
	s_and_b64 s[26:27], s[24:25], exec
	v_readfirstlane_b32 s26, v122
	s_cselect_b32 s26, s26, s36
	s_lshl_b32 s37, s26, 6
	s_add_i32 s40, s30, 0xffffffbf
	s_and_b64 s[26:27], s[24:25], exec
	s_cselect_b32 s26, s29, s40
	s_lshl_b32 s26, s26, 6
	s_add_i32 s40, s26, s33
	s_cmp_gt_u32 s31, 3
	s_cselect_b64 s[26:27], -1, 0
	s_add_i32 s37, s37, s7
	s_and_b64 s[34:35], s[34:35], exec
	s_cselect_b32 s34, s40, s37
	s_waitcnt vmcnt(4)
	ds_write_b128 v251, v[94:97]
	s_waitcnt vmcnt(3)
	ds_write_b128 v251, v[98:101] offset:17408
	ds_write_b128 v251, v[102:105] offset:34816
	ds_write_b128 v250, v[110:113]
	s_waitcnt vmcnt(2)
	ds_write_b128 v250, v[106:109] offset:17408
	s_waitcnt vmcnt(1)
	ds_write_b128 v250, v[114:117] offset:34816
	s_waitcnt vmcnt(0)
	ds_write_b16 v249, v118 offset:52224
	ds_write_b16_d16_hi v249, v118 offset:52368
	ds_write_b16 v249, v119 offset:52512
	ds_write_b16_d16_hi v249, v119 offset:52656
	ds_write_b16 v249, v120 offset:52800
	ds_write_b16_d16_hi v249, v120 offset:52944
	ds_write_b16 v249, v121 offset:53088
	ds_write_b16_d16_hi v249, v121 offset:53232
	v_add_u32_e32 v94, s34, v237
	v_add_u32_e32 v106, s34, v238
	v_ashrrev_i32_e32 v95, 31, v94
	v_ashrrev_i32_e32 v107, 31, v106
	v_lshlrev_b64 v[94:95], 11, v[94:95]
	v_lshlrev_b64 v[106:107], 11, v[106:107]
	v_lshl_add_u64 v[94:95], v[94:95], 0, v[200:201]
	v_lshl_add_u64 v[106:107], v[106:107], 0, v[200:201]
	v_or_b32_e32 v118, s34, v185
	v_lshlrev_b64 v[102:103], 1, v[94:95]
	v_lshlrev_b64 v[114:115], 1, v[106:107]
	v_ashrrev_i32_e32 v119, 31, v118
	s_waitcnt lgkmcnt(0)
	s_barrier
	ds_read_b64_tr_b16 v[122:123], v245 offset:34816
	ds_read_b64_tr_b16 v[124:125], v245 offset:35904
	ds_read_b64_tr_b16 v[138:139], v245 offset:43520
	ds_read_b64_tr_b16 v[140:141], v245 offset:44608
	v_lshl_add_u64 v[94:95], v[188:189], 0, v[102:103]
	v_lshl_add_u64 v[98:99], v[196:197], 0, v[102:103]
	v_lshl_add_u64 v[102:103], v[198:199], 0, v[102:103]
	v_lshl_add_u64 v[106:107], v[188:189], 0, v[114:115]
	v_lshlrev_b64 v[118:119], 12, v[118:119]
	global_load_dwordx4 v[102:105], v[102:103], off
	v_lshl_add_u64 v[118:119], v[216:217], 0, v[118:119]
	global_load_dwordx4 v[110:113], v[106:107], off
	v_lshl_add_u64 v[106:107], v[196:197], 0, v[114:115]
	v_lshl_add_u64 v[114:115], v[198:199], 0, v[114:115]
	global_load_dwordx4 v[94:97], v[94:95], off
	v_mov_b32_e32 v126, 0x3f803f80
	global_load_dwordx4 v[98:101], v[98:99], off
	s_or_b64 s[34:35], s[4:5], s[26:27]
	global_load_dwordx4 v[106:109], v[106:107], off
	s_and_b64 vcc, exec, s[34:35]
	global_load_dwordx4 v[114:117], v[114:115], off
	s_nop 0
	global_load_dwordx4 v[118:121], v[118:119], off
	v_mov_b32_e32 v127, v126
	v_mov_b32_e32 v128, v126
	v_mov_b32_e32 v129, v126
	s_waitcnt lgkmcnt(2)
	v_mfma_f32_16x16x32_bf16 v[142:145], v[122:125], v[10:13], v[2:5]
	v_mfma_f32_16x16x32_bf16 v[146:149], v[122:125], v[6:9], v[2:5]
	v_mfma_f32_16x16x32_bf16 v[122:125], v[122:125], v[126:129], v[2:5]
	s_waitcnt lgkmcnt(0)
	v_mfma_f32_16x16x32_bf16 v[134:137], v[138:141], v[10:13], v[122:125]
	v_mfma_f32_16x16x32_bf16 v[130:133], v[138:141], v[6:9], v[122:125]
	s_nop 4
	v_sub_f32_e32 v145, v145, v125
	v_sub_f32_e32 v144, v144, v124
	v_sub_f32_e32 v143, v143, v123
	v_mfma_f32_16x16x32_bf16 v[126:129], v[138:141], v[126:129], v[122:125]
	v_mul_f32_e32 v138, 0x3fb8aa3b, v122
	v_mul_f32_e32 v139, 0x3fb8aa3b, v123
	v_mul_f32_e32 v140, 0x3fb8aa3b, v124
	v_mul_f32_e32 v141, 0x3fb8aa3b, v125
	v_exp_f32_e32 v138, v138
	v_exp_f32_e32 v139, v139
	v_exp_f32_e32 v140, v140
	v_exp_f32_e32 v141, v141
	v_sub_f32_e32 v142, v142, v122
	v_pk_mul_f32 v[152:153], v[214:215], v[138:139]
	v_med3_f32 v142, v142, s95, v182
	v_pk_mul_f32 v[150:151], v[218:219], v[140:141]
	v_cvt_pk_bf16_f32 v152, v152, v153
	v_cvt_pk_bf16_f32 v153, v150, v151
	ds_write_b64 v246, v[152:153]
	v_pk_mul_f32 v[150:151], v[212:213], v[140:141]
	v_pk_mul_f32 v[152:153], v[210:211], v[138:139]
	v_med3_f32 v143, v143, s95, v182
	v_cvt_pk_bf16_f32 v152, v152, v153
	v_cvt_pk_bf16_f32 v153, v150, v151
	v_med3_f32 v144, v144, s95, v182
	v_med3_f32 v145, v145, s95, v182
	ds_write_b64 v246, v[152:153] offset:4352
	v_pk_mul_f32 v[150:151], v[208:209], v[140:141]
	v_pk_mul_f32 v[152:153], v[206:207], v[138:139]
	v_pk_mul_f32 v[140:141], v[204:205], v[140:141]
	v_pk_mul_f32 v[138:139], v[202:203], v[138:139]
	v_pk_mul_f32 v[144:145], v[144:145], s[56:57] op_sel_hi:[1,0]
	v_pk_mul_f32 v[142:143], v[142:143], s[56:57] op_sel_hi:[1,0]
	v_cvt_pk_bf16_f32 v152, v152, v153
	v_cvt_pk_bf16_f32 v153, v150, v151
	v_cvt_pk_bf16_f32 v138, v138, v139
	v_cvt_pk_bf16_f32 v139, v140, v141
	v_exp_f32_e32 v142, v142
	v_exp_f32_e32 v143, v143
	v_exp_f32_e32 v144, v144
	v_exp_f32_e32 v145, v145
	ds_write_b64 v246, v[152:153] offset:8704
	ds_write_b64 v246, v[138:139] offset:13056
	ds_read_b64 v[138:139], v247
	ds_read_b64 v[140:141], v247 offset:17408
	v_rcp_f32_e32 v150, v142
	v_rcp_f32_e32 v151, v143
	v_rcp_f32_e32 v152, v144
	v_rcp_f32_e32 v153, v145
	s_waitcnt lgkmcnt(1)
	v_lshlrev_b32_e32 v154, 16, v138
	v_and_b32_e32 v155, 0xffff0000, v138
	v_lshlrev_b32_e32 v138, 16, v139
	v_and_b32_e32 v139, 0xffff0000, v139
	v_pk_mul_f32 v[138:139], v[144:145], v[138:139]
	v_pk_mul_f32 v[142:143], v[142:143], v[154:155]
	s_waitcnt lgkmcnt(0)
; #define LAS __attribute__((address_space(3)))
; __device__ __forceinline__ unsigned pk2(float lo, float hi) { const f32x2_t v = {lo, hi}; const bf16x2_t b = __builtin_convertvector(v, bf16x2_t); return __builtin_bit_cast(unsigned, b); }
; #define MX_BAR() do { asm volatile("s_waitcnt lgkmcnt(0)" ::: "memory"); __builtin_amdgcn_s_barrier(); if (MXP_BAR > 1) __builtin_amdgcn_s_barrier(); asm volatile("" ::: "memory"); } while (0)
; __device__ __forceinline__ void mixer_hg2(const Args& a, Frame& F, bool ctx_out) {
;     ...
;                 for (int t = 0; t < 4; ++t) {
;                     LAS unsigned char* pq = L + (16 * t + i) * QS + (16 * w + 4 * g) * 2;
;                     const v2u qw = *(const LAS v2u*)pq, kw = *(const LAS v2u*)(pq + IMG);
;                     const f32x4 dd = ct[t] - cref;
;                     const f32x4 tt = (f32x4){__builtin_amdgcn_fmed3f(dd[0], -80.f, 80.f), __builtin_amdgcn_fmed3f(dd[1], -80.f, 80.f), __builtin_amdgcn_fmed3f(dd[2], -80.f, 80.f), __builtin_amdgcn_fmed3f(dd[3], -80.f, 80.f)} * 1.4426950408889634f;
;                     const f32x4 e1 = {__builtin_amdgcn_exp2f(tt[0]), __builtin_amdgcn_exp2f(tt[1]), __builtin_amdgcn_exp2f(tt[2]), __builtin_amdgcn_exp2f(tt[3])};
;                     const f32x4 e2 = {__builtin_amdgcn_rcpf(e1[0]), __builtin_amdgcn_rcpf(e1[1]), __builtin_amdgcn_rcpf(e1[2]), __builtin_amdgcn_rcpf(e1[3])};
;                     const f32x4 q4 = (f32x4){bflo(qw.x), bfhi(qw.x), bflo(qw.y), bfhi(qw.y)} * e1, k4 = (f32x4){bflo(kw.x), bfhi(kw.x), bflo(kw.y), bfhi(kw.y)} * e2;
;                     v2u qo, ko;
;                     qo.x = pk2(q4[0], q4[1]); qo.y = pk2(q4[2], q4[3]);
;                     ko.x = pk2(k4[0], k4[1]); ko.y = pk2(k4[2], k4[3]);
;                     *(LAS v2u*)pq = qo; *(LAS v2u*)(pq + IMG) = ko;
;                 }
;             }
;             MX_BAR();
;             const int rlo = H2_ROWLO(c);
;             const bool do_out = ctx_out || c >= NCTX;
;             mx_bf16x8 aq[KS];
;             {
;                 mx_bf16x8 kf[2][KS], vt[4][2];
;                 if (do_out) {
; #pragma unroll
;                     for (int ks = 0; ks < KS; ++ks) { aq[ks] = frag_row(L, QS, nq0, 32 * ks, lane); kf[0][ks] = frag_row(L + IMG, QS, 32 * cg, 32 * ks, lane); kf[1][ks] = frag_row(L + IMG, QS, 32 * cg + 16, 32 * ks, lane); }
	v_lshlrev_b32_e32 v144, 16, v140
	v_and_b32_e32 v145, 0xffff0000, v140
	v_lshlrev_b32_e32 v140, 16, v141
	v_and_b32_e32 v141, 0xffff0000, v141
	v_pk_mul_f32 v[140:141], v[152:153], v[140:141]
	v_pk_mul_f32 v[144:145], v[150:151], v[144:145]
	v_cvt_pk_bf16_f32 v142, v142, v143
	v_cvt_pk_bf16_f32 v143, v138, v139
	v_cvt_pk_bf16_f32 v138, v144, v145
	v_cvt_pk_bf16_f32 v139, v140, v141
	ds_write_b64 v247, v[142:143]
	ds_write_b64 v247, v[138:139] offset:17408
	v_sub_f32_e32 v145, v149, v125
	v_sub_f32_e32 v144, v148, v124
	v_sub_f32_e32 v143, v147, v123
	v_sub_f32_e32 v142, v146, v122
	v_med3_f32 v142, v142, s95, v182
	v_med3_f32 v143, v143, s95, v182
	v_med3_f32 v144, v144, s95, v182
	v_med3_f32 v145, v145, s95, v182
	v_pk_mul_f32 v[144:145], v[144:145], s[56:57] op_sel_hi:[1,0]
	v_pk_mul_f32 v[142:143], v[142:143], s[56:57] op_sel_hi:[1,0]
	v_exp_f32_e32 v144, v144
	v_exp_f32_e32 v142, v142
	v_exp_f32_e32 v143, v143
	v_exp_f32_e32 v145, v145
	ds_read_b64 v[138:139], v247 offset:4352
	ds_read_b64 v[140:141], v247 offset:21760
	v_rcp_f32_e32 v146, v142
	v_rcp_f32_e32 v147, v143
	v_rcp_f32_e32 v148, v144
	v_rcp_f32_e32 v149, v145
	v_sub_f32_e32 v137, v137, v125
	v_sub_f32_e32 v136, v136, v124
	v_sub_f32_e32 v135, v135, v123
	v_sub_f32_e32 v134, v134, v122
	s_waitcnt lgkmcnt(1)
	v_lshlrev_b32_e32 v150, 16, v138
	v_and_b32_e32 v151, 0xffff0000, v138
	v_lshlrev_b32_e32 v138, 16, v139
	v_and_b32_e32 v139, 0xffff0000, v139
	v_med3_f32 v134, v134, s95, v182
	v_med3_f32 v135, v135, s95, v182
	v_med3_f32 v136, v136, s95, v182
	v_med3_f32 v137, v137, s95, v182
	v_pk_mul_f32 v[138:139], v[144:145], v[138:139]
	v_pk_mul_f32 v[142:143], v[142:143], v[150:151]
	s_waitcnt lgkmcnt(0)
	v_lshlrev_b32_e32 v144, 16, v140
	v_and_b32_e32 v145, 0xffff0000, v140
	v_lshlrev_b32_e32 v140, 16, v141
	v_and_b32_e32 v141, 0xffff0000, v141
	v_pk_mul_f32 v[136:137], v[136:137], s[56:57] op_sel_hi:[1,0]
	v_pk_mul_f32 v[134:135], v[134:135], s[56:57] op_sel_hi:[1,0]
	v_pk_mul_f32 v[140:141], v[148:149], v[140:141]
	v_pk_mul_f32 v[144:145], v[146:147], v[144:145]
	v_cvt_pk_bf16_f32 v142, v142, v143
	v_cvt_pk_bf16_f32 v143, v138, v139
	v_exp_f32_e32 v134, v134
	v_exp_f32_e32 v135, v135
	v_exp_f32_e32 v136, v136
	v_exp_f32_e32 v137, v137
	v_cvt_pk_bf16_f32 v138, v144, v145
	v_cvt_pk_bf16_f32 v139, v140, v141
	ds_write_b64 v247, v[142:143] offset:4352
	ds_write_b64 v247, v[138:139] offset:21760
	ds_read_b64 v[138:139], v247 offset:8704
	ds_read_b64 v[140:141], v247 offset:26112
	v_rcp_f32_e32 v142, v134
	v_rcp_f32_e32 v143, v135
	v_rcp_f32_e32 v144, v136
	v_rcp_f32_e32 v145, v137
	v_sub_f32_e32 v133, v133, v125
	v_sub_f32_e32 v132, v132, v124
	v_sub_f32_e32 v131, v131, v123
	v_sub_f32_e32 v130, v130, v122
	s_waitcnt lgkmcnt(1)
	v_lshlrev_b32_e32 v146, 16, v138
	v_and_b32_e32 v147, 0xffff0000, v138
	v_lshlrev_b32_e32 v138, 16, v139
	v_and_b32_e32 v139, 0xffff0000, v139
	v_med3_f32 v130, v130, s95, v182
	v_med3_f32 v131, v131, s95, v182
	v_med3_f32 v132, v132, s95, v182
	v_med3_f32 v133, v133, s95, v182
	v_pk_mul_f32 v[136:137], v[136:137], v[138:139]
	v_pk_mul_f32 v[134:135], v[134:135], v[146:147]
	s_waitcnt lgkmcnt(0)
	v_lshlrev_b32_e32 v138, 16, v140
	v_and_b32_e32 v139, 0xffff0000, v140
	v_lshlrev_b32_e32 v140, 16, v141
	v_and_b32_e32 v141, 0xffff0000, v141
	v_pk_mul_f32 v[132:133], v[132:133], s[56:57] op_sel_hi:[1,0]
	v_pk_mul_f32 v[130:131], v[130:131], s[56:57] op_sel_hi:[1,0]
	v_pk_mul_f32 v[140:141], v[144:145], v[140:141]
	v_pk_mul_f32 v[138:139], v[142:143], v[138:139]
	v_cvt_pk_bf16_f32 v134, v134, v135
	v_cvt_pk_bf16_f32 v135, v136, v137
	v_exp_f32_e32 v130, v130
	v_exp_f32_e32 v131, v131
	v_exp_f32_e32 v132, v132
	v_exp_f32_e32 v133, v133
	v_cvt_pk_bf16_f32 v136, v138, v139
	v_cvt_pk_bf16_f32 v137, v140, v141
	ds_write_b64 v247, v[134:135] offset:8704
	ds_write_b64 v247, v[136:137] offset:26112
	ds_read_b64 v[134:135], v247 offset:13056
	ds_read_b64 v[136:137], v247 offset:30464
	v_rcp_f32_e32 v138, v130
	v_rcp_f32_e32 v139, v131
	v_rcp_f32_e32 v140, v132
	v_rcp_f32_e32 v141, v133
	s_waitcnt lgkmcnt(1)
	v_lshlrev_b32_e32 v142, 16, v134
	v_and_b32_e32 v143, 0xffff0000, v134
	v_lshlrev_b32_e32 v134, 16, v135
	v_and_b32_e32 v135, 0xffff0000, v135
	v_pk_mul_f32 v[132:133], v[132:133], v[134:135]
	v_pk_mul_f32 v[130:131], v[130:131], v[142:143]
	s_waitcnt lgkmcnt(0)
	v_lshlrev_b32_e32 v134, 16, v136
	v_and_b32_e32 v135, 0xffff0000, v136
	v_lshlrev_b32_e32 v136, 16, v137
	v_and_b32_e32 v137, 0xffff0000, v137
	v_pk_mul_f32 v[136:137], v[140:141], v[136:137]
	v_pk_mul_f32 v[134:135], v[138:139], v[134:135]
	v_cvt_pk_bf16_f32 v130, v130, v131
	v_cvt_pk_bf16_f32 v131, v132, v133
	v_cvt_pk_bf16_f32 v132, v134, v135
	v_cvt_pk_bf16_f32 v133, v136, v137
	ds_write_b64 v247, v[130:131] offset:13056
	ds_write_b64 v247, v[132:133] offset:30464
	s_waitcnt lgkmcnt(0)
	s_barrier
	s_cbranch_vccz .LBB0_514
	v_add_u32_e32 v42, v230, v232
	v_add_u32_e32 v54, v231, v232
	ds_read_b128 v[14:17], v42
	ds_read_b128 v[18:21], v42 offset:64
	ds_read_b128 v[30:33], v54 offset:17408
	ds_read_b128 v[38:41], v54 offset:17472
	ds_read_b128 v[26:29], v54 offset:21760
	ds_read_b128 v[34:37], v54 offset:21824
	ds_read_b128 v[22:25], v42 offset:128
	ds_read_b128 v[42:45], v42 offset:192
	ds_read_b128 v[50:53], v54 offset:17536
	ds_read_b128 v[58:61], v54 offset:17600
	ds_read_b128 v[46:49], v54 offset:21888
	ds_read_b128 v[54:57], v54 offset:21952

;     ...
;             MX_STAGE(u);
;             if (MXP_STG > 1) { asm volatile("" ::: "memory"); MX_STAGE(u); }
;             if (HG) {
;                 MX_BAR();
;                 const int d = tid & 127, qr = tid >> 7;
;                 float cl[16], qv[16], kv[16]; float run = 0.f;
; #pragma unroll
;                 for (int ii = 0; ii < 16; ++ii) { const int s = 16 * qr + ii;
;                     const int eo = s * QS + 16 * ((d >> 3) ^ sw16(s)) + (d & 7) * 2;
;                     run += bflo((unsigned)*(const LAS unsigned short*)(L + 2 * IMG + eo)); cl[ii] = run;
;                     qv[ii] = bflo((unsigned)*(const LAS unsigned short*)(L + eo)); kv[ii] = bflo((unsigned)*(const LAS unsigned short*)(L + IMG + eo)); }
;                 LAS float* tot = (LAS float*)(L + O_TOT);
;                 tot[qr * 128 + d] = run;
;                 MX_BAR();
;                 const float t0 = tot[d], t1 = tot[128 + d], t2 = tot[256 + d], t3 = tot[384 + d];
;                 const float off = (qr == 0) ? 0.f : (qr == 1) ? t0 : (qr == 2) ? (t0 + t1) : (t0 + t1 + t2);
;                 const float cref = t0 + t1, cend = (t0 + t1) + (t2 + t3);
;                 if (qr == 0) tot[512 + d] = cend;
; #pragma unroll
;                 for (int ii = 0; ii < 16; ++ii) { const int s = 16 * qr + ii; const float cm = off + cl[ii]; const int eo = s * QS + 16 * ((d >> 3) ^ sw16(s)) + (d & 7) * 2;
;                     const float e1 = __expf(fminf(cm - cref, 80.f)), e2 = __expf(fminf(cref - cm, 80.f)), e3 = __expf(cm), e4 = __expf(cend - cm);
;                     const unsigned w12 = pk2(qv[ii] * e1, kv[ii] * e2), w34 = pk2(qv[ii] * e3, kv[ii] * e4);
;                     *(LAS unsigned short*)(L + eo) = (unsigned short)(w12 & 0xffffu);
;                     *(LAS unsigned short*)(L + IMG + eo) = (unsigned short)(w12 >> 16);
;                     *(LAS unsigned short*)(L + 2 * IMG + eo) = (unsigned short)(w34 & 0xffffu);
;                     *(LAS unsigned short*)(L + 3 * IMG + eo) = (unsigned short)(w34 >> 16); }
;             }
;             MX_BAR();
;             { const int cn = (c + PF < NCH) ? c + PF : NCH - 1; MX_LOAD(cn, u); }
;             if (MXP_SLEEP > 0) __builtin_amdgcn_s_sleep(MXP_SLEEP);
;             const int rlo = MX_ROWLO(c);
;             const bool do_out = ctx_out || c >= NCTX;
;             mx_bf16x8 aq[KS];
;             if (do_out) {
; #pragma unroll
.LBB0_803:
	s_add_i32 s31, s27, 1
	s_add_i32 s34, s35, -1
	v_sub_co_u32_e64 v178, s[36:37], s27, 3
	s_and_b64 s[28:29], s[24:25], exec
	s_waitcnt vmcnt(7)
	ds_write_b128 v191, v[66:69]
	s_waitcnt vmcnt(6)
	ds_write_b128 v191, v[74:77] offset:33792
	s_waitcnt vmcnt(5)
	ds_write_b128 v190, v[78:81]
	s_waitcnt vmcnt(4)
	ds_write_b128 v190, v[86:89] offset:33792
	s_waitcnt vmcnt(3)
	ds_write_b128 v189, v[90:93]
	s_waitcnt vmcnt(2)
	ds_write_b128 v189, v[94:97] offset:33792
	s_waitcnt vmcnt(1)
	ds_write_b128 v188, v[98:101]
	s_waitcnt vmcnt(0)
	ds_write_b128 v188, v[102:105] offset:33792
	v_lshlrev_b32_e32 v66, 16, v58
	v_and_b32_e32 v67, 0xffff0000, v58
	v_readfirstlane_b32 s28, v178
	v_pk_mul_f32 v[66:67], v[136:137], v[66:67]
	s_cselect_b32 s28, s28, s34
	v_cvt_pk_bf16_f32 v58, v66, v67
	s_lshl_b32 s40, s28, 6
	s_add_i32 s41, s35, 0xffffffbf
	ds_write_b16 v177, v58
	ds_write_b16_d16_hi v187, v58 offset:144
	v_lshlrev_b32_e32 v58, 16, v59
	v_and_b32_e32 v59, 0xffff0000, v59
	s_and_b64 s[28:29], s[24:25], exec
	v_pk_mul_f32 v[58:59], v[136:137], v[58:59]
	s_cselect_b32 s28, s31, s41
	v_cvt_pk_bf16_f32 v58, v58, v59
	s_lshl_b32 s28, s28, 6
	ds_write_b16 v177, v58 offset:288
	ds_write_b16_d16_hi v186, v58 offset:144
	v_lshlrev_b32_e32 v58, 16, v60
	v_and_b32_e32 v59, 0xffff0000, v60
	s_add_i32 s41, s28, s26
	v_pk_mul_f32 v[58:59], v[136:137], v[58:59]
	s_cmp_gt_u32 s27, 3
	v_cvt_pk_bf16_f32 v58, v58, v59
	s_cselect_b64 s[28:29], -1, 0
	ds_write_b16 v177, v58 offset:576
	ds_write_b16_d16_hi v185, v58 offset:144
	v_lshlrev_b32_e32 v58, 16, v61
	v_and_b32_e32 v59, 0xffff0000, v61
	s_add_i32 s40, s40, s30
	v_pk_mul_f32 v[58:59], v[136:137], v[58:59]
	s_and_b64 s[36:37], s[36:37], exec
	v_cvt_pk_bf16_f32 v58, v58, v59
	s_cselect_b32 s36, s41, s40
	ds_write_b16 v177, v58 offset:864
	ds_write_b16_d16_hi v184, v58 offset:144
	v_add_u32_e32 v58, s36, v149
	v_ashrrev_i32_e32 v59, 31, v58
	v_lshlrev_b64 v[58:59], 11, v[58:59]
	v_lshl_add_u64 v[58:59], v[58:59], 0, v[138:139]
	v_lshlrev_b64 v[58:59], 1, v[58:59]
	s_waitcnt lgkmcnt(0)
	s_barrier
	s_or_b64 s[28:29], s[4:5], s[28:29]
	s_and_b64 vcc, exec, s[28:29]
	s_cbranch_vccz .Lret_skiprd
	v_add_u32_e32 v34, v152, v117
	v_add_u32_e32 v178, v153, v117
	ds_read_b128 v[6:9], v34
	ds_read_b128 v[10:13], v34 offset:64
	ds_read_b128 v[14:17], v34 offset:128
	ds_read_b128 v[18:21], v34 offset:192
	ds_read_b128 v[22:25], v34 offset:256
	ds_read_b128 v[26:29], v34 offset:320
	ds_read_b128 v[30:33], v34 offset:384
	ds_read_b128 v[34:37], v34 offset:448
	ds_read_b128 v[192:195], v178 offset:33792
	ds_read_b128 v[196:199], v178 offset:33856
	ds_read_b128 v[200:203], v178 offset:42240
	ds_read_b128 v[204:207], v178 offset:42304
	ds_read_b128 v[208:211], v178 offset:33920
	ds_read_b128 v[212:215], v178 offset:33984
	ds_read_b128 v[216:219], v178 offset:42368
	ds_read_b128 v[228:231], v178 offset:42432
.Lret_skiprd:
	v_lshl_add_u64 v[60:61], v[106:107], 0, v[58:59]
	v_lshl_add_u64 v[58:59], v[108:109], 0, v[58:59]
	global_load_dwordx4 v[66:69], v[60:61], off
	global_load_dwordx4 v[74:77], v[58:59], off
	v_add_u32_e32 v58, s36, v156
	v_ashrrev_i32_e32 v59, 31, v58
	v_lshlrev_b64 v[58:59], 11, v[58:59]
	v_lshl_add_u64 v[58:59], v[58:59], 0, v[140:141]
	v_lshlrev_b64 v[58:59], 1, v[58:59]
	v_lshl_add_u64 v[60:61], v[106:107], 0, v[58:59]
	v_lshl_add_u64 v[58:59], v[108:109], 0, v[58:59]
	global_load_dwordx4 v[78:81], v[60:61], off
	global_load_dwordx4 v[86:89], v[58:59], off
	v_add_u32_e32 v58, s36, v161
	v_ashrrev_i32_e32 v59, 31, v58
	v_lshlrev_b64 v[58:59], 11, v[58:59]
	v_lshl_add_u64 v[58:59], v[58:59], 0, v[142:143]
	v_lshlrev_b64 v[58:59], 1, v[58:59]
	v_lshl_add_u64 v[60:61], v[106:107], 0, v[58:59]
	v_lshl_add_u64 v[58:59], v[108:109], 0, v[58:59]
	global_load_dwordx4 v[90:93], v[60:61], off
	global_load_dwordx4 v[94:97], v[58:59], off
	v_add_u32_e32 v58, s36, v163
	v_ashrrev_i32_e32 v59, 31, v58
	v_lshlrev_b64 v[58:59], 11, v[58:59]
	v_lshl_add_u64 v[58:59], v[58:59], 0, v[144:145]
	v_lshlrev_b64 v[58:59], 1, v[58:59]
	v_lshl_add_u64 v[60:61], v[106:107], 0, v[58:59]
	v_lshl_add_u64 v[58:59], v[108:109], 0, v[58:59]
	global_load_dwordx4 v[98:101], v[60:61], off
	global_load_dwordx4 v[102:105], v[58:59], off
	v_or_b32_e32 v58, s36, v113
	v_ashrrev_i32_e32 v59, 31, v58
	v_lshlrev_b64 v[58:59], 12, v[58:59]
	v_lshl_add_u64 v[58:59], v[146:147], 0, v[58:59]
	global_load_dwordx4 v[58:61], v[58:59], off
	s_cbranch_vccz .LBB0_805
	s_waitcnt lgkmcnt(7)
	v_mfma_f32_16x16x32_bf16 v[192:195], v[192:195], v[6:9], v[2:5]
	s_waitcnt lgkmcnt(5)
	v_mfma_f32_16x16x32_bf16 v[200:203], v[200:203], v[6:9], v[2:5]
	v_mfma_f32_16x16x32_bf16 v[192:195], v[196:199], v[10:13], v[192:195]
	s_waitcnt lgkmcnt(4)
	v_mfma_f32_16x16x32_bf16 v[196:199], v[204:207], v[10:13], v[200:203]
	s_waitcnt lgkmcnt(3)
	v_mfma_f32_16x16x32_bf16 v[192:195], v[208:211], v[14:17], v[192:195]
	s_waitcnt lgkmcnt(1)
	v_mfma_f32_16x16x32_bf16 v[196:199], v[216:219], v[14:17], v[196:199]
	v_mfma_f32_16x16x32_bf16 v[192:195], v[212:215], v[18:21], v[192:195]
	s_waitcnt lgkmcnt(0)
	v_mfma_f32_16x16x32_bf16 v[196:199], v[228:231], v[18:21], v[196:199]
	ds_read_b128 v[200:203], v178 offset:34048
	ds_read_b128 v[204:207], v178 offset:34112
	ds_read_b128 v[208:211], v178 offset:42496
	ds_read_b128 v[212:215], v178 offset:42560
	ds_read_b128 v[216:219], v178 offset:34176
	ds_read_b128 v[228:231], v178 offset:34240
	ds_read_b128 v[232:235], v178 offset:42624
	ds_read_b128 v[236:239], v178 offset:42688
	s_waitcnt lgkmcnt(7)
	v_mfma_f32_16x16x32_bf16 v[192:195], v[200:203], v[22:25], v[192:195]
	s_waitcnt lgkmcnt(5)
	v_mfma_f32_16x16x32_bf16 v[196:199], v[208:211], v[22:25], v[196:199]
	v_mfma_f32_16x16x32_bf16 v[192:195], v[204:207], v[26:29], v[192:195]
	s_waitcnt lgkmcnt(4)
	v_mfma_f32_16x16x32_bf16 v[196:199], v[212:215], v[26:29], v[196:199]
	s_waitcnt lgkmcnt(3)
	v_mfma_f32_16x16x32_bf16 v[192:195], v[216:219], v[30:33], v[192:195]
	s_waitcnt lgkmcnt(1)
	v_mfma_f32_16x16x32_bf16 v[196:199], v[232:235], v[30:33], v[196:199]
	v_mfma_f32_16x16x32_bf16 v[192:195], v[228:231], v[34:37], v[192:195]
	s_waitcnt lgkmcnt(0)
	v_mfma_f32_16x16x32_bf16 v[196:199], v[236:239], v[34:37], v[196:199]
	s_nop 5
	v_cndmask_b32_e64 v178, v192, 0, s[8:9]
	v_cndmask_b32_e64 v179, 0, v193, s[10:11]
	v_cvt_pk_bf16_f32 v178, v178, v179
	v_cndmask_b32_e64 v179, v194, 0, s[12:13]
	v_cndmask_b32_e64 v180, v195, 0, s[14:15]
	v_cvt_pk_bf16_f32 v179, v179, v180
	v_add_u32_e32 v180, v158, v148
	ds_write_b64 v180, v[178:179]
	v_cndmask_b32_e64 v178, v196, 0, s[16:17]
	v_cndmask_b32_e64 v179, v197, 0, s[18:19]
	v_cvt_pk_bf16_f32 v178, v178, v179
	v_cndmask_b32_e64 v179, v198, 0, s[20:21]
	v_cndmask_b32_e64 v180, v199, 0, s[22:23]
	v_cvt_pk_bf16_f32 v179, v179, v180
	v_add_u32_e32 v180, v159, v148
	ds_write_b64 v180, v[178:179]
